# SWA unit prologue: first K/V tile, Q and sink loads issued before the bias-table load/wait (three serial round trips become one)
# speedup vs baseline: 1.0059x; 1.0059x over previous
; DI float bf2f(unsigned short u) { return __uint_as_float((unsigned)u << 16); }
; #define ATT_LBAR() asm volatile("s_waitcnt lgkmcnt(0)\n\ts_barrier" ::: "memory")
; template <int MODE> DI void attn_unit(int b, int qb, const bf16* Qb, int qpitch, const bf16* Kb, int kpitch, const bf16* VT, bf16* O, float* ssq, ...
;     ...
;     if (MODE == 0) { if (tid < 320) { const int dist = 223 - tid; MS[tid] = ((unsigned)dist < 128u) ? aux[dist & 127] : NEGBIG; } }
;     ATT_LBAR();
;     v8s qr[ND];
; #pragma unroll
;     for (int d0 = 0; d0 < ND; ++d0) qr[d0] = *(const v8s*)(Qb + (rowbase + q) * qpitch + 16 * d0 + 8 * hi);
;     const int kt_lo = (MODE == 0) ? (4 * qb - 2 > 0 ? 4 * qb - 2 : 0) : 0, kt_hi = 4 * qb + 3;
;     v4u kreg0, kreg1 = {}, vreg; float freg = 0.f;
;     const int krow0 = tid / PCS, kc0 = tid % PCS, krow1 = (tid + 512) / PCS, kc1 = (tid + 512) % PCS;
;     const int vd = tid >> 3, vc = tid & 7;
;     ...
;     constexpr bool REV = (MODE == 1);
;     const int ntile = kt_hi - kt_lo + 1;
;     float qn = 0.f;
;     if (REV) {
; #pragma unroll
;         for (int d0 = 0; d0 < ND; ++d0)
; #pragma unroll
;             for (int j = 0; j < 8; ++j) { const float f = bf2f((unsigned short)qr[d0][j]); qn += f * f; }
;         qn += __shfl_xor(qn, 32); qn = sqrtf(qn) * 1.01f;
;     }
;     ATT_LOAD(REV ? kt_hi : kt_lo); ATT_STORE(0);
;     ATT_LBAR();
;     float m = (MODE == 0) ? aux2[0] * LOG2E : NEGBIG;
.LBB0_525:
	s_or_b32 s18, s24, s23
	s_lshl_b32 s25, s18, 8
	s_lshl_b32 s21, s18, 2
	s_add_i32 s25, s25, s3
	s_add_i32 s19, s21, -2
	s_cmp_lg_u32 s18, 0
	s_cselect_b32 s20, s19, 0
	v_or_b32_e32 v0, s25, v119
	v_mov_b32_e32 v1, v65
	s_lshl_b32 s18, s20, 6
	s_mov_b32 s19, s73
	v_lshl_add_u64 v[160:161], s[12:13], 0, v[0:1]
	v_lshl_add_u64 v[0:1], v[94:95], 0, s[18:19]
	v_lshlrev_b64 v[0:1], 12, v[0:1]
	v_lshl_add_u64 v[0:1], v[96:97], 0, v[0:1]
	v_lshl_add_u64 v[2:3], s[18:19], 1, v[98:99]
	global_load_dwordx4 v[82:85], v[0:1], off
	global_load_dwordx4 v[86:89], v[2:3], off
	v_lshlrev_b64 v[0:1], 12, v[160:161]
	v_lshl_add_u64 v[0:1], v[92:93], 0, v[0:1]
	global_load_dwordx4 v[66:69], v[0:1], off
	global_load_dwordx4 v[70:73], v[0:1], off offset:32
	global_load_dwordx4 v[74:77], v[0:1], off offset:64
	global_load_dwordx4 v[78:81], v[0:1], off offset:96
	global_load_dword v250, v65, s[16:17]
	s_and_saveexec_b64 s[98:99], s[52:53]
	s_cbranch_execz .LBB0_529
	v_mov_b32_e32 v0, 0xf149f2ca
	s_and_saveexec_b64 s[100:101], s[54:55]
	s_cbranch_execz .LBB0_528
	global_load_dword v0, v[90:91], off
.LBB0_528:
	s_or_b64 exec, exec, s[100:101]
	s_waitcnt vmcnt(0)
	ds_write_b32 v198, v0 offset:36352
.LBB0_529:
	s_or_b64 exec, exec, s[98:99]
	s_waitcnt lgkmcnt(0)
	s_barrier
	s_or_b32 s19, s21, 3
	s_sub_i32 s26, s19, s20
	s_cmp_lt_i32 s26, 0
	s_waitcnt vmcnt(6)
	ds_write_b128 v197, v[82:85]
	s_waitcnt vmcnt(5)
	ds_write2_b64 v159, v[86:87], v[88:89] offset1:1
	s_waitcnt lgkmcnt(0)
	s_barrier
	s_cbranch_scc1 .LBB0_540
	v_mov_b32_e32 v14, v65
	v_mov_b32_e32 v15, v65
	v_mov_b32_e32 v1, v65
	v_mov_b32_e32 v2, v65
	v_mov_b32_e32 v3, v65
	v_mov_b32_e32 v4, v65
	v_mov_b32_e32 v5, v65
	v_mov_b32_e32 v6, v65
	v_mov_b32_e32 v7, v65
	v_mov_b32_e32 v8, v65
	v_mov_b32_e32 v9, v65
	v_mov_b32_e32 v10, v65
	v_mov_b32_e32 v11, v65
	v_mov_b32_e32 v12, v65
	v_mov_b32_e32 v13, v65
	s_or_b32 s27, s25, 31
	s_add_i32 s36, s25, 0xffffff81
	s_sub_i32 s58, s22, s20
	v_lshl_add_u32 v153, s20, 8, v162
	s_mov_b32 s59, 0
	v_mov_b32_e32 v155, v201
	s_mov_b32 s60, 0
	s_waitcnt vmcnt(0)
	v_mul_f32_e32 v157, 0x3fb8aa3b, v250
	v_mov_b32_e32 v0, v65
	v_mov_b64_e32 v[30:31], v[14:15]
	v_mov_b64_e32 v[28:29], v[12:13]
	v_mov_b64_e32 v[26:27], v[10:11]
	v_mov_b64_e32 v[24:25], v[8:9]
	v_mov_b64_e32 v[22:23], v[6:7]
	v_mov_b64_e32 v[20:21], v[4:5]
	v_mov_b64_e32 v[18:19], v[2:3]
	v_mov_b64_e32 v[16:17], v[0:1]
	s_branch .LBB0_532
